# residual-GEMM epilogue de-serialised: all base loads before first store, counted vmcnt
# speedup vs baseline: 1.0075x; 1.0075x over previous
; #define PG8_GAS __attribute__((address_space(1)))
; __device__ __forceinline__ unsigned cvtpk(float lo, float hi) { f32x2 v = {lo, hi}; bf16x2_t b = __builtin_convertvector(v, bf16x2_t); return __builtin_bit_cast(unsigned, b); }
; template <class T> __device__ __forceinline__ GAS T* gp(T* p) { return (GAS T*)p; }
;     __device__ __forceinline__ void operator()(const f32x4 (&acc)[2][2][4][2], const Unit& u, int wr, int wc, int fr, int fq) const {
;         const int b = (u.pm * BM) >> 13;
;         const float* gp = mod + b * 9216 + step * 3072 + 2048; const float coef = step == 1 ? 1.0f : 0.5f;
;         const float* basef = step == 0 ? xin : (const float*)nullptr; const bf16_t* baseb = xs; bf16_t* out = xs;
;         const int col0 = u.pn * BM + wc * 32 + 8 * fq;
;         f32x4 gv[2][2];
; #pragma unroll
;         for (int bj = 0; bj < 2; ++bj)
; #pragma unroll
;             for (int n = 0; n < 2; ++n) gv[bj][n] = (*(const PG8_GAS f32x4*)(gp + col0 + bj * HALF + 4 * n) + 1.0f) * coef;
; #pragma unroll
;         for (int ai = 0; ai < 2; ++ai)
; #pragma unroll
;             for (int m = 0; m < 4; ++m) {
;                 const size_t off = (size_t)(u.pm * BM + ai * HALF + wr * 64 + m * 16 + fr) * 1024 + col0;
; #pragma unroll
;                 for (int bj = 0; bj < 2; ++bj) {
;                     f32x4 b0, b1;
;                     if (basef) { b0 = __builtin_nontemporal_load((const PG8_GAS f32x4*)(basef + off + bj * HALF)); b1 = __builtin_nontemporal_load((const PG8_GAS f32x4*)(basef + off + bj * HALF + 4)); }
;                     else { const u32x4 w = __builtin_nontemporal_load((const PG8_GAS u32x4*)(baseb + off + bj * HALF));
;                         b0 = (f32x4){__uint_as_float(w.x << 16), __uint_as_float(w.x & 0xffff0000u), __uint_as_float(w.y << 16), __uint_as_float(w.y & 0xffff0000u)};
;                         b1 = (f32x4){__uint_as_float(w.z << 16), __uint_as_float(w.z & 0xffff0000u), __uint_as_float(w.w << 16), __uint_as_float(w.w & 0xffff0000u)}; }
;                     const f32x4 o0 = b0 + gv[bj][0] * acc[ai][bj][m][0], o1 = b1 + gv[bj][1] * acc[ai][bj][m][1];
;                     u32x4 w; w.x = cvtpk(o0[0], o0[1]); w.y = cvtpk(o0[2], o0[3]); w.z = cvtpk(o1[0], o1[1]); w.w = cvtpk(o1[2], o1[3]);
;                     __builtin_nontemporal_store(w, (PG8_GAS u32x4*)(out + off + bj * HALF));
.LBB0_628:
	s_lshr_b32 s4, s25, 5
	s_mulk_i32 s4, 0x2400
	s_ashr_i32 s5, s4, 31
	s_lshl_b64 s[4:5], s[4:5], 2
	s_add_u32 s4, s38, s4
	v_lshl_or_b32 v2, s40, 8, v178
	s_addc_u32 s5, s18, s5
	v_ashrrev_i32_e32 v3, 31, v2
	v_lshl_add_u64 v[134:135], v[2:3], 2, s[4:5]
	s_mov_b64 s[4:5], 0x2000
	v_lshl_add_u64 v[138:139], v[134:135], 0, s[4:5]
	v_add_co_u32_e32 v134, vcc, s47, v134
	v_add_u32_e32 v170, s42, v176
	s_nop 0
	v_addc_co_u32_e32 v135, vcc, 0, v135, vcc
	global_load_dwordx4 v[146:149], v[134:135], off
	s_nop 0
	global_load_dwordx4 v[134:137], v[138:139], off offset:528
	global_load_dwordx4 v[142:145], v[138:139], off offset:16
	s_nop 0
	global_load_dwordx4 v[138:141], v[138:139], off offset:512
	v_ashrrev_i32_e32 v171, 31, v170
	v_lshlrev_b64 v[150:151], 10, v[170:171]
	v_lshl_add_u64 v[150:151], v[150:151], 0, v[2:3]
	v_lshl_add_u64 v[2:3], v[150:151], 1, s[56:57]
	v_lshl_add_u64 v[174:175], v[150:151], 2, s[64:65]
	v_mov_b64_e32 v[182:183], v[2:3]
	s_andn2_b64 vcc, exec, s[66:67]
	s_cbranch_vccnz .Lres_epi_bf16
	s_mov_b32 s4, 0x10000
	s_mov_b32 s5, 0
	s_mov_b32 vcc_lo, 0x50000
	s_mov_b32 vcc_hi, 0
	global_load_dwordx4 v[150:153], v[174:175], off nt
	global_load_dwordx4 v[154:157], v[174:175], off offset:16 nt
	global_load_dwordx4 v[170:173], v[174:175], off offset:512 nt
	global_load_dwordx4 v[184:187], v[174:175], off offset:528 nt
	v_lshl_add_u64 v[174:175], v[174:175], 0, s[4:5]
	global_load_dwordx4 v[188:191], v[174:175], off nt
	global_load_dwordx4 v[192:195], v[174:175], off offset:16 nt
	global_load_dwordx4 v[208:211], v[174:175], off offset:512 nt
	global_load_dwordx4 v[226:229], v[174:175], off offset:528 nt
	v_lshl_add_u64 v[174:175], v[174:175], 0, s[4:5]
	global_load_dwordx4 v[230:233], v[174:175], off nt
	global_load_dwordx4 v[234:237], v[174:175], off offset:16 nt
	global_load_dwordx4 v[238:241], v[174:175], off offset:512 nt
	global_load_dwordx4 v[242:245], v[174:175], off offset:528 nt
	v_lshl_add_u64 v[174:175], v[174:175], 0, s[4:5]
	global_load_dwordx4 v[246:249], v[174:175], off nt
	global_load_dwordx4 v[250:253], v[174:175], off offset:16 nt
	s_waitcnt vmcnt(12)
	v_pk_add_f32 v[148:149], v[148:149], 1.0 op_sel_hi:[1,0]
	v_pk_add_f32 v[180:181], v[146:147], 1.0 op_sel_hi:[1,0]
	v_pk_mul_f32 v[146:147], s[60:61], v[148:149]
	v_pk_mul_f32 v[148:149], s[10:11], v[180:181]
	v_pk_add_f32 v[180:181], v[142:143], 1.0 op_sel_hi:[1,0]
	v_pk_add_f32 v[142:143], v[144:145], 1.0 op_sel_hi:[1,0]
	v_pk_mul_f32 v[144:145], s[10:11], v[180:181]
	v_pk_mul_f32 v[142:143], s[60:61], v[142:143]
	v_pk_add_f32 v[140:141], v[140:141], 1.0 op_sel_hi:[1,0]
	v_pk_add_f32 v[180:181], v[138:139], 1.0 op_sel_hi:[1,0]
	v_pk_mul_f32 v[138:139], s[60:61], v[140:141]
	v_pk_mul_f32 v[140:141], s[10:11], v[180:181]
	v_pk_add_f32 v[180:181], v[134:135], 1.0 op_sel_hi:[1,0]
	v_pk_add_f32 v[134:135], v[136:137], 1.0 op_sel_hi:[1,0]
	v_pk_mul_f32 v[136:137], s[10:11], v[180:181]
	v_pk_mul_f32 v[134:135], s[60:61], v[134:135]
	v_pk_fma_f32 v[130:131], v[130:131], v[148:149], v[150:151]
	v_pk_fma_f32 v[132:133], v[132:133], v[146:147], v[152:153]
	v_pk_fma_f32 v[126:127], v[126:127], v[144:145], v[154:155]
	v_pk_fma_f32 v[128:129], v[128:129], v[142:143], v[156:157]
	v_cvt_pk_bf16_f32 v130, v130, v131
	v_cvt_pk_bf16_f32 v131, v132, v133
	v_cvt_pk_bf16_f32 v132, v126, v127
	v_cvt_pk_bf16_f32 v133, v128, v129
	global_load_dwordx4 v[150:153], v[174:175], off offset:512 nt
	global_load_dwordx4 v[154:157], v[174:175], off offset:528 nt
	v_lshl_add_u64 v[174:175], v[174:175], 0, vcc
	s_waitcnt vmcnt(12)
	v_pk_fma_f32 v[122:123], v[122:123], v[140:141], v[170:171]
	v_pk_fma_f32 v[124:125], v[124:125], v[138:139], v[172:173]
	v_pk_fma_f32 v[118:119], v[118:119], v[136:137], v[184:185]
	v_pk_fma_f32 v[120:121], v[120:121], v[134:135], v[186:187]
	v_cvt_pk_bf16_f32 v122, v122, v123
	v_cvt_pk_bf16_f32 v123, v124, v125
	v_cvt_pk_bf16_f32 v124, v118, v119
	v_cvt_pk_bf16_f32 v125, v120, v121
	global_load_dwordx4 v[126:129], v[174:175], off nt
	global_load_dwordx4 v[170:173], v[174:175], off offset:16 nt
	global_load_dwordx4 v[184:187], v[174:175], off offset:512 nt
	global_load_dwordx4 v[118:121], v[174:175], off offset:528 nt
	v_lshl_add_u64 v[174:175], v[174:175], 0, s[4:5]
	s_waitcnt vmcnt(14)
	v_pk_fma_f32 v[114:115], v[114:115], v[148:149], v[188:189]
	v_pk_fma_f32 v[116:117], v[116:117], v[146:147], v[190:191]
	v_pk_fma_f32 v[110:111], v[110:111], v[144:145], v[192:193]
	v_pk_fma_f32 v[112:113], v[112:113], v[142:143], v[194:195]
	v_cvt_pk_bf16_f32 v114, v114, v115
	v_cvt_pk_bf16_f32 v115, v116, v117
	v_cvt_pk_bf16_f32 v116, v110, v111
	v_cvt_pk_bf16_f32 v117, v112, v113
	global_load_dwordx4 v[188:191], v[174:175], off nt
	global_load_dwordx4 v[192:195], v[174:175], off offset:16 nt
	s_waitcnt vmcnt(14)
	v_pk_fma_f32 v[106:107], v[106:107], v[140:141], v[208:209]
	v_pk_fma_f32 v[108:109], v[108:109], v[138:139], v[210:211]
	v_pk_fma_f32 v[102:103], v[102:103], v[136:137], v[226:227]
	v_pk_fma_f32 v[104:105], v[104:105], v[134:135], v[228:229]
	v_cvt_pk_bf16_f32 v106, v106, v107
	v_cvt_pk_bf16_f32 v107, v108, v109
	v_cvt_pk_bf16_f32 v108, v102, v103
	v_cvt_pk_bf16_f32 v109, v104, v105
	global_load_dwordx4 v[110:113], v[174:175], off offset:512 nt
	global_load_dwordx4 v[208:211], v[174:175], off offset:528 nt
	v_lshl_add_u64 v[174:175], v[174:175], 0, s[4:5]
	global_load_dwordx4 v[226:229], v[174:175], off nt
	global_load_dwordx4 v[102:105], v[174:175], off offset:16 nt
	s_waitcnt vmcnt(16)
; #define PG8_GAS __attribute__((address_space(1)))
; __device__ __forceinline__ unsigned cvtpk(float lo, float hi) { f32x2 v = {lo, hi}; bf16x2_t b = __builtin_convertvector(v, bf16x2_t); return __builtin_bit_cast(unsigned, b); }
;     __device__ __forceinline__ void operator()(const f32x4 (&acc)[2][2][4][2], const Unit& u, int wr, int wc, int fr, int fq) const {
;     ...
;         for (int ai = 0; ai < 2; ++ai)
; #pragma unroll
;             for (int m = 0; m < 4; ++m) {
;                 const size_t off = (size_t)(u.pm * BM + ai * HALF + wr * 64 + m * 16 + fr) * 1024 + col0;
; #pragma unroll
;                 for (int bj = 0; bj < 2; ++bj) {
;                     f32x4 b0, b1;
;                     if (basef) { b0 = __builtin_nontemporal_load((const PG8_GAS f32x4*)(basef + off + bj * HALF)); b1 = __builtin_nontemporal_load((const PG8_GAS f32x4*)(basef + off + bj * HALF + 4)); }
;                     else { const u32x4 w = __builtin_nontemporal_load((const PG8_GAS u32x4*)(baseb + off + bj * HALF));
;                         b0 = (f32x4){__uint_as_float(w.x << 16), __uint_as_float(w.x & 0xffff0000u), __uint_as_float(w.y << 16), __uint_as_float(w.y & 0xffff0000u)};
;                         b1 = (f32x4){__uint_as_float(w.z << 16), __uint_as_float(w.z & 0xffff0000u), __uint_as_float(w.w << 16), __uint_as_float(w.w & 0xffff0000u)}; }
;                     const f32x4 o0 = b0 + gv[bj][0] * acc[ai][bj][m][0], o1 = b1 + gv[bj][1] * acc[ai][bj][m][1];
;                     u32x4 w; w.x = cvtpk(o0[0], o0[1]); w.y = cvtpk(o0[2], o0[3]); w.z = cvtpk(o1[0], o1[1]); w.w = cvtpk(o1[2], o1[3]);
;                     __builtin_nontemporal_store(w, (PG8_GAS u32x4*)(out + off + bj * HALF));
;                 }
	v_pk_fma_f32 v[98:99], v[98:99], v[148:149], v[230:231]
	v_pk_fma_f32 v[100:101], v[100:101], v[146:147], v[232:233]
	v_pk_fma_f32 v[94:95], v[94:95], v[144:145], v[234:235]
	v_pk_fma_f32 v[96:97], v[96:97], v[142:143], v[236:237]
	v_cvt_pk_bf16_f32 v98, v98, v99
	v_cvt_pk_bf16_f32 v99, v100, v101
	v_cvt_pk_bf16_f32 v100, v94, v95
	v_cvt_pk_bf16_f32 v101, v96, v97
	global_load_dwordx4 v[230:233], v[174:175], off offset:512 nt
	global_load_dwordx4 v[234:237], v[174:175], off offset:528 nt
	v_lshl_add_u64 v[174:175], v[174:175], 0, s[4:5]
	s_waitcnt vmcnt(16)
	v_pk_fma_f32 v[90:91], v[90:91], v[140:141], v[238:239]
	v_pk_fma_f32 v[92:93], v[92:93], v[138:139], v[240:241]
	v_pk_fma_f32 v[86:87], v[86:87], v[136:137], v[242:243]
	v_pk_fma_f32 v[88:89], v[88:89], v[134:135], v[244:245]
	v_cvt_pk_bf16_f32 v90, v90, v91
	v_cvt_pk_bf16_f32 v91, v92, v93
	v_cvt_pk_bf16_f32 v92, v86, v87
	v_cvt_pk_bf16_f32 v93, v88, v89
	global_load_dwordx4 v[94:97], v[174:175], off nt
	global_load_dwordx4 v[238:241], v[174:175], off offset:16 nt
	global_load_dwordx4 v[242:245], v[174:175], off offset:512 nt
	global_load_dwordx4 v[86:89], v[174:175], off offset:528 nt
	s_mov_b32 s4, 0x8000
	s_mov_b32 vcc_lo, 0x28000
	global_store_dwordx4 v[2:3], v[130:133], off nt
	global_store_dwordx4 v[2:3], v[122:125], off offset:256 nt
	v_lshl_add_u64 v[2:3], v[2:3], 0, s[4:5]
	global_store_dwordx4 v[2:3], v[114:117], off nt
	global_store_dwordx4 v[2:3], v[106:109], off offset:256 nt
	v_lshl_add_u64 v[2:3], v[2:3], 0, s[4:5]
	global_store_dwordx4 v[2:3], v[98:101], off nt
	global_store_dwordx4 v[2:3], v[90:93], off offset:256 nt
	v_lshl_add_u64 v[2:3], v[2:3], 0, s[4:5]
	s_waitcnt vmcnt(24)
	v_pk_fma_f32 v[82:83], v[82:83], v[148:149], v[246:247]
	v_pk_fma_f32 v[84:85], v[84:85], v[146:147], v[248:249]
	v_pk_fma_f32 v[78:79], v[78:79], v[144:145], v[250:251]
	v_pk_fma_f32 v[80:81], v[80:81], v[142:143], v[252:253]
	v_cvt_pk_bf16_f32 v82, v82, v83
	v_cvt_pk_bf16_f32 v83, v84, v85
	v_cvt_pk_bf16_f32 v84, v78, v79
	v_cvt_pk_bf16_f32 v85, v80, v81
	global_store_dwordx4 v[2:3], v[82:85], off nt
	s_waitcnt vmcnt(23)
	v_pk_fma_f32 v[74:75], v[74:75], v[140:141], v[150:151]
	v_pk_fma_f32 v[76:77], v[76:77], v[138:139], v[152:153]
	v_pk_fma_f32 v[70:71], v[70:71], v[136:137], v[154:155]
	v_pk_fma_f32 v[72:73], v[72:73], v[134:135], v[156:157]
	v_cvt_pk_bf16_f32 v74, v74, v75
	v_cvt_pk_bf16_f32 v75, v76, v77
	v_cvt_pk_bf16_f32 v76, v70, v71
	v_cvt_pk_bf16_f32 v77, v72, v73
	global_store_dwordx4 v[2:3], v[74:77], off offset:256 nt
	v_lshl_add_u64 v[2:3], v[2:3], 0, vcc
	s_waitcnt vmcnt(22)
	v_pk_fma_f32 v[66:67], v[66:67], v[148:149], v[126:127]
	v_pk_fma_f32 v[68:69], v[68:69], v[146:147], v[128:129]
	v_pk_fma_f32 v[62:63], v[62:63], v[144:145], v[170:171]
	v_pk_fma_f32 v[64:65], v[64:65], v[142:143], v[172:173]
	v_cvt_pk_bf16_f32 v66, v66, v67
	v_cvt_pk_bf16_f32 v67, v68, v69
	v_cvt_pk_bf16_f32 v68, v62, v63
	v_cvt_pk_bf16_f32 v69, v64, v65
	global_store_dwordx4 v[2:3], v[66:69], off nt
	s_waitcnt vmcnt(21)
	v_pk_fma_f32 v[58:59], v[58:59], v[140:141], v[184:185]
	v_pk_fma_f32 v[60:61], v[60:61], v[138:139], v[186:187]
	v_pk_fma_f32 v[54:55], v[54:55], v[136:137], v[118:119]
	v_pk_fma_f32 v[56:57], v[56:57], v[134:135], v[120:121]
	v_cvt_pk_bf16_f32 v58, v58, v59
	v_cvt_pk_bf16_f32 v59, v60, v61
	v_cvt_pk_bf16_f32 v60, v54, v55
	v_cvt_pk_bf16_f32 v61, v56, v57
	global_store_dwordx4 v[2:3], v[58:61], off offset:256 nt
	v_lshl_add_u64 v[2:3], v[2:3], 0, s[4:5]
	s_waitcnt vmcnt(20)
	v_pk_fma_f32 v[50:51], v[50:51], v[148:149], v[188:189]
	v_pk_fma_f32 v[52:53], v[52:53], v[146:147], v[190:191]
	v_pk_fma_f32 v[46:47], v[46:47], v[144:145], v[192:193]
	v_pk_fma_f32 v[48:49], v[48:49], v[142:143], v[194:195]
	v_cvt_pk_bf16_f32 v50, v50, v51
	v_cvt_pk_bf16_f32 v51, v52, v53
	v_cvt_pk_bf16_f32 v52, v46, v47
	v_cvt_pk_bf16_f32 v53, v48, v49
	global_store_dwordx4 v[2:3], v[50:53], off nt
	s_waitcnt vmcnt(19)
	v_pk_fma_f32 v[42:43], v[42:43], v[140:141], v[110:111]
	v_pk_fma_f32 v[44:45], v[44:45], v[138:139], v[112:113]
	v_pk_fma_f32 v[38:39], v[38:39], v[136:137], v[208:209]
	v_pk_fma_f32 v[40:41], v[40:41], v[134:135], v[210:211]
	v_cvt_pk_bf16_f32 v42, v42, v43
	v_cvt_pk_bf16_f32 v43, v44, v45
	v_cvt_pk_bf16_f32 v44, v38, v39
	v_cvt_pk_bf16_f32 v45, v40, v41
	global_store_dwordx4 v[2:3], v[42:45], off offset:256 nt
	v_lshl_add_u64 v[2:3], v[2:3], 0, s[4:5]
	s_waitcnt vmcnt(18)
	v_pk_fma_f32 v[34:35], v[34:35], v[148:149], v[226:227]
	v_pk_fma_f32 v[36:37], v[36:37], v[146:147], v[228:229]
	v_pk_fma_f32 v[30:31], v[30:31], v[144:145], v[102:103]
	v_pk_fma_f32 v[32:33], v[32:33], v[142:143], v[104:105]
	v_cvt_pk_bf16_f32 v34, v34, v35
	v_cvt_pk_bf16_f32 v35, v36, v37
	v_cvt_pk_bf16_f32 v36, v30, v31
	v_cvt_pk_bf16_f32 v37, v32, v33
	global_store_dwordx4 v[2:3], v[34:37], off nt
	s_waitcnt vmcnt(17)
	v_pk_fma_f32 v[26:27], v[26:27], v[140:141], v[230:231]
	v_pk_fma_f32 v[28:29], v[28:29], v[138:139], v[232:233]
	v_pk_fma_f32 v[22:23], v[22:23], v[136:137], v[234:235]
	v_pk_fma_f32 v[24:25], v[24:25], v[134:135], v[236:237]
	v_cvt_pk_bf16_f32 v26, v26, v27
	v_cvt_pk_bf16_f32 v27, v28, v29
	v_cvt_pk_bf16_f32 v28, v22, v23
	v_cvt_pk_bf16_f32 v29, v24, v25
	global_store_dwordx4 v[2:3], v[26:29], off offset:256 nt
	v_lshl_add_u64 v[2:3], v[2:3], 0, s[4:5]
	s_waitcnt vmcnt(16)
	v_pk_fma_f32 v[18:19], v[18:19], v[148:149], v[94:95]
	v_pk_fma_f32 v[20:21], v[20:21], v[146:147], v[96:97]
	v_pk_fma_f32 v[14:15], v[14:15], v[144:145], v[238:239]
	v_pk_fma_f32 v[16:17], v[16:17], v[142:143], v[240:241]
	v_cvt_pk_bf16_f32 v18, v18, v19
	v_cvt_pk_bf16_f32 v19, v20, v21
	v_cvt_pk_bf16_f32 v20, v14, v15
	v_cvt_pk_bf16_f32 v21, v16, v17
	global_store_dwordx4 v[2:3], v[18:21], off nt
	s_waitcnt vmcnt(15)
	v_pk_fma_f32 v[10:11], v[10:11], v[140:141], v[242:243]
	v_pk_fma_f32 v[12:13], v[12:13], v[138:139], v[244:245]
	v_pk_fma_f32 v[6:7], v[6:7], v[136:137], v[86:87]
	v_pk_fma_f32 v[8:9], v[8:9], v[134:135], v[88:89]
	v_cvt_pk_bf16_f32 v10, v10, v11
	v_cvt_pk_bf16_f32 v11, v12, v13
	v_cvt_pk_bf16_f32 v12, v6, v7
	v_cvt_pk_bf16_f32 v13, v8, v9
	s_and_b64 vcc, exec, s[6:7]
	s_mov_b64 s[4:5], -1
	global_store_dwordx4 v[2:3], v[10:13], off offset:256 nt
	s_branch .Lres_epi_tail
; #define PG8_GAS __attribute__((address_space(1)))
; __device__ __forceinline__ unsigned cvtpk(float lo, float hi) { f32x2 v = {lo, hi}; bf16x2_t b = __builtin_convertvector(v, bf16x2_t); return __builtin_bit_cast(unsigned, b); }
; template <class T> __device__ __forceinline__ GAS T* gp(T* p) { return (GAS T*)p; }
;     __device__ __forceinline__ void operator()(const f32x4 (&acc)[2][2][4][2], const Unit& u, int wr, int wc, int fr, int fq) const {
;     ...
;         for (int bj = 0; bj < 2; ++bj)
; #pragma unroll
;             for (int n = 0; n < 2; ++n) gv[bj][n] = (*(const PG8_GAS f32x4*)(gp + col0 + bj * HALF + 4 * n) + 1.0f) * coef;
; #pragma unroll
;         for (int ai = 0; ai < 2; ++ai)
; #pragma unroll
;             for (int m = 0; m < 4; ++m) {
;                 const size_t off = (size_t)(u.pm * BM + ai * HALF + wr * 64 + m * 16 + fr) * 1024 + col0;
; #pragma unroll
;                 for (int bj = 0; bj < 2; ++bj) {
;                     f32x4 b0, b1;
;                     if (basef) { b0 = __builtin_nontemporal_load((const PG8_GAS f32x4*)(basef + off + bj * HALF)); b1 = __builtin_nontemporal_load((const PG8_GAS f32x4*)(basef + off + bj * HALF + 4)); }
;                     else { const u32x4 w = __builtin_nontemporal_load((const PG8_GAS u32x4*)(baseb + off + bj * HALF));
;                         b0 = (f32x4){__uint_as_float(w.x << 16), __uint_as_float(w.x & 0xffff0000u), __uint_as_float(w.y << 16), __uint_as_float(w.y & 0xffff0000u)};
;                         b1 = (f32x4){__uint_as_float(w.z << 16), __uint_as_float(w.z & 0xffff0000u), __uint_as_float(w.w << 16), __uint_as_float(w.w & 0xffff0000u)}; }
;                     const f32x4 o0 = b0 + gv[bj][0] * acc[ai][bj][m][0], o1 = b1 + gv[bj][1] * acc[ai][bj][m][1];
;                     u32x4 w; w.x = cvtpk(o0[0], o0[1]); w.y = cvtpk(o0[2], o0[3]); w.z = cvtpk(o1[0], o1[1]); w.w = cvtpk(o1[2], o1[3]);
;                     __builtin_nontemporal_store(w, (PG8_GAS u32x4*)(out + off + bj * HALF));
.Lres_epi_bf16:
	s_mov_b32 s4, 0x8000
	s_mov_b32 s5, 0
	s_mov_b32 vcc_lo, 0x28000
	s_mov_b32 vcc_hi, 0
	global_load_dwordx4 v[150:153], v[182:183], off nt
	global_load_dwordx4 v[154:157], v[182:183], off offset:256 nt
	v_lshl_add_u64 v[182:183], v[182:183], 0, s[4:5]
	global_load_dwordx4 v[170:173], v[182:183], off nt
	global_load_dwordx4 v[184:187], v[182:183], off offset:256 nt
	v_lshl_add_u64 v[182:183], v[182:183], 0, s[4:5]
	global_load_dwordx4 v[188:191], v[182:183], off nt
	global_load_dwordx4 v[192:195], v[182:183], off offset:256 nt
	v_lshl_add_u64 v[182:183], v[182:183], 0, s[4:5]
	global_load_dwordx4 v[208:211], v[182:183], off nt
	global_load_dwordx4 v[226:229], v[182:183], off offset:256 nt
	v_lshl_add_u64 v[182:183], v[182:183], 0, vcc
	global_load_dwordx4 v[230:233], v[182:183], off nt
	global_load_dwordx4 v[234:237], v[182:183], off offset:256 nt
	v_lshl_add_u64 v[182:183], v[182:183], 0, s[4:5]
	global_load_dwordx4 v[238:241], v[182:183], off nt
	global_load_dwordx4 v[242:245], v[182:183], off offset:256 nt
	v_lshl_add_u64 v[182:183], v[182:183], 0, s[4:5]
	global_load_dwordx4 v[246:249], v[182:183], off nt
	global_load_dwordx4 v[250:253], v[182:183], off offset:256 nt
	v_lshl_add_u64 v[182:183], v[182:183], 0, s[4:5]
	s_waitcnt vmcnt(13)
	v_pk_add_f32 v[148:149], v[148:149], 1.0 op_sel_hi:[1,0]
	v_pk_add_f32 v[180:181], v[146:147], 1.0 op_sel_hi:[1,0]
	v_pk_mul_f32 v[146:147], s[60:61], v[148:149]
	v_pk_mul_f32 v[148:149], s[10:11], v[180:181]
	v_pk_add_f32 v[180:181], v[142:143], 1.0 op_sel_hi:[1,0]
	v_pk_add_f32 v[142:143], v[144:145], 1.0 op_sel_hi:[1,0]
	v_pk_mul_f32 v[144:145], s[10:11], v[180:181]
	v_pk_mul_f32 v[142:143], s[60:61], v[142:143]
	v_pk_add_f32 v[140:141], v[140:141], 1.0 op_sel_hi:[1,0]
	v_pk_add_f32 v[180:181], v[138:139], 1.0 op_sel_hi:[1,0]
	v_pk_mul_f32 v[138:139], s[60:61], v[140:141]
	v_pk_mul_f32 v[140:141], s[10:11], v[180:181]
	v_pk_add_f32 v[180:181], v[134:135], 1.0 op_sel_hi:[1,0]
	v_pk_add_f32 v[134:135], v[136:137], 1.0 op_sel_hi:[1,0]
	v_pk_mul_f32 v[136:137], s[10:11], v[180:181]
	v_pk_mul_f32 v[134:135], s[60:61], v[134:135]
	v_lshlrev_b32_e32 v180, 16, v150
	v_and_b32_e32 v181, 0xffff0000, v150
	v_pk_fma_f32 v[130:131], v[130:131], v[148:149], v[180:181]
	v_lshlrev_b32_e32 v150, 16, v151
	v_and_b32_e32 v151, 0xffff0000, v151
	v_pk_fma_f32 v[132:133], v[132:133], v[146:147], v[150:151]
	v_lshlrev_b32_e32 v180, 16, v152
	v_and_b32_e32 v181, 0xffff0000, v152
	v_pk_fma_f32 v[126:127], v[126:127], v[144:145], v[180:181]
	v_lshlrev_b32_e32 v152, 16, v153
	v_and_b32_e32 v153, 0xffff0000, v153
	v_pk_fma_f32 v[128:129], v[128:129], v[142:143], v[152:153]
	v_cvt_pk_bf16_f32 v130, v130, v131
	v_cvt_pk_bf16_f32 v131, v132, v133
	v_cvt_pk_bf16_f32 v132, v126, v127
	v_cvt_pk_bf16_f32 v133, v128, v129
	global_load_dwordx4 v[150:153], v[182:183], off nt
	global_load_dwordx4 v[126:129], v[182:183], off offset:256 nt
	global_store_dwordx4 v[2:3], v[130:133], off nt
	s_waitcnt vmcnt(15)
	v_lshlrev_b32_e32 v180, 16, v154
	v_and_b32_e32 v181, 0xffff0000, v154
	v_pk_fma_f32 v[122:123], v[122:123], v[140:141], v[180:181]
	v_lshlrev_b32_e32 v154, 16, v155
	v_and_b32_e32 v155, 0xffff0000, v155
	v_pk_fma_f32 v[124:125], v[124:125], v[138:139], v[154:155]
	v_lshlrev_b32_e32 v180, 16, v156
	v_and_b32_e32 v181, 0xffff0000, v156
	v_pk_fma_f32 v[118:119], v[118:119], v[136:137], v[180:181]
	v_lshlrev_b32_e32 v156, 16, v157
	v_and_b32_e32 v157, 0xffff0000, v157
	v_pk_fma_f32 v[120:121], v[120:121], v[134:135], v[156:157]
	v_cvt_pk_bf16_f32 v122, v122, v123
	v_cvt_pk_bf16_f32 v123, v124, v125
	v_cvt_pk_bf16_f32 v124, v118, v119
	v_cvt_pk_bf16_f32 v125, v120, v121
	global_store_dwordx4 v[2:3], v[122:125], off offset:256 nt
	v_lshl_add_u64 v[2:3], v[2:3], 0, s[4:5]
	s_waitcnt vmcnt(15)
	v_lshlrev_b32_e32 v180, 16, v170
	v_and_b32_e32 v181, 0xffff0000, v170
	v_pk_fma_f32 v[114:115], v[114:115], v[148:149], v[180:181]
	v_lshlrev_b32_e32 v170, 16, v171
	v_and_b32_e32 v171, 0xffff0000, v171
	v_pk_fma_f32 v[116:117], v[116:117], v[146:147], v[170:171]
	v_lshlrev_b32_e32 v180, 16, v172
	v_and_b32_e32 v181, 0xffff0000, v172
	v_pk_fma_f32 v[110:111], v[110:111], v[144:145], v[180:181]
	v_lshlrev_b32_e32 v172, 16, v173
	v_and_b32_e32 v173, 0xffff0000, v173
	v_pk_fma_f32 v[112:113], v[112:113], v[142:143], v[172:173]
	v_cvt_pk_bf16_f32 v114, v114, v115
	v_cvt_pk_bf16_f32 v115, v116, v117
	v_cvt_pk_bf16_f32 v116, v110, v111
	v_cvt_pk_bf16_f32 v117, v112, v113
	global_store_dwordx4 v[2:3], v[114:117], off nt
	s_waitcnt vmcnt(15)
	v_lshlrev_b32_e32 v180, 16, v184
	v_and_b32_e32 v181, 0xffff0000, v184
	v_pk_fma_f32 v[106:107], v[106:107], v[140:141], v[180:181]
	v_lshlrev_b32_e32 v184, 16, v185
	v_and_b32_e32 v185, 0xffff0000, v185
	v_pk_fma_f32 v[108:109], v[108:109], v[138:139], v[184:185]
	v_lshlrev_b32_e32 v180, 16, v186
	v_and_b32_e32 v181, 0xffff0000, v186
	v_pk_fma_f32 v[102:103], v[102:103], v[136:137], v[180:181]
	v_lshlrev_b32_e32 v186, 16, v187
	v_and_b32_e32 v187, 0xffff0000, v187
	v_pk_fma_f32 v[104:105], v[104:105], v[134:135], v[186:187]
	v_cvt_pk_bf16_f32 v106, v106, v107
	v_cvt_pk_bf16_f32 v107, v108, v109
	v_cvt_pk_bf16_f32 v108, v102, v103
	v_cvt_pk_bf16_f32 v109, v104, v105
	global_store_dwordx4 v[2:3], v[106:109], off offset:256 nt
	v_lshl_add_u64 v[2:3], v[2:3], 0, s[4:5]
	s_waitcnt vmcnt(15)
; #define PG8_GAS __attribute__((address_space(1)))
; __device__ __forceinline__ unsigned cvtpk(float lo, float hi) { f32x2 v = {lo, hi}; bf16x2_t b = __builtin_convertvector(v, bf16x2_t); return __builtin_bit_cast(unsigned, b); }
;     __device__ __forceinline__ void operator()(const f32x4 (&acc)[2][2][4][2], const Unit& u, int wr, int wc, int fr, int fq) const {
;     ...
;                 for (int bj = 0; bj < 2; ++bj) {
;                     f32x4 b0, b1;
;                     if (basef) { b0 = __builtin_nontemporal_load((const PG8_GAS f32x4*)(basef + off + bj * HALF)); b1 = __builtin_nontemporal_load((const PG8_GAS f32x4*)(basef + off + bj * HALF + 4)); }
;                     else { const u32x4 w = __builtin_nontemporal_load((const PG8_GAS u32x4*)(baseb + off + bj * HALF));
;                         b0 = (f32x4){__uint_as_float(w.x << 16), __uint_as_float(w.x & 0xffff0000u), __uint_as_float(w.y << 16), __uint_as_float(w.y & 0xffff0000u)};
;                         b1 = (f32x4){__uint_as_float(w.z << 16), __uint_as_float(w.z & 0xffff0000u), __uint_as_float(w.w << 16), __uint_as_float(w.w & 0xffff0000u)}; }
;                     const f32x4 o0 = b0 + gv[bj][0] * acc[ai][bj][m][0], o1 = b1 + gv[bj][1] * acc[ai][bj][m][1];
;                     u32x4 w; w.x = cvtpk(o0[0], o0[1]); w.y = cvtpk(o0[2], o0[3]); w.z = cvtpk(o1[0], o1[1]); w.w = cvtpk(o1[2], o1[3]);
;                     __builtin_nontemporal_store(w, (PG8_GAS u32x4*)(out + off + bj * HALF));
	v_lshlrev_b32_e32 v180, 16, v188
	v_and_b32_e32 v181, 0xffff0000, v188
	v_pk_fma_f32 v[98:99], v[98:99], v[148:149], v[180:181]
	v_lshlrev_b32_e32 v188, 16, v189
	v_and_b32_e32 v189, 0xffff0000, v189
	v_pk_fma_f32 v[100:101], v[100:101], v[146:147], v[188:189]
	v_lshlrev_b32_e32 v180, 16, v190
	v_and_b32_e32 v181, 0xffff0000, v190
	v_pk_fma_f32 v[94:95], v[94:95], v[144:145], v[180:181]
	v_lshlrev_b32_e32 v190, 16, v191
	v_and_b32_e32 v191, 0xffff0000, v191
	v_pk_fma_f32 v[96:97], v[96:97], v[142:143], v[190:191]
	v_cvt_pk_bf16_f32 v98, v98, v99
	v_cvt_pk_bf16_f32 v99, v100, v101
	v_cvt_pk_bf16_f32 v100, v94, v95
	v_cvt_pk_bf16_f32 v101, v96, v97
	global_store_dwordx4 v[2:3], v[98:101], off nt
	s_waitcnt vmcnt(15)
	v_lshlrev_b32_e32 v180, 16, v192
	v_and_b32_e32 v181, 0xffff0000, v192
	v_pk_fma_f32 v[90:91], v[90:91], v[140:141], v[180:181]
	v_lshlrev_b32_e32 v192, 16, v193
	v_and_b32_e32 v193, 0xffff0000, v193
	v_pk_fma_f32 v[92:93], v[92:93], v[138:139], v[192:193]
	v_lshlrev_b32_e32 v180, 16, v194
	v_and_b32_e32 v181, 0xffff0000, v194
	v_pk_fma_f32 v[86:87], v[86:87], v[136:137], v[180:181]
	v_lshlrev_b32_e32 v194, 16, v195
	v_and_b32_e32 v195, 0xffff0000, v195
	v_pk_fma_f32 v[88:89], v[88:89], v[134:135], v[194:195]
	v_cvt_pk_bf16_f32 v90, v90, v91
	v_cvt_pk_bf16_f32 v91, v92, v93
	v_cvt_pk_bf16_f32 v92, v86, v87
	v_cvt_pk_bf16_f32 v93, v88, v89
	global_store_dwordx4 v[2:3], v[90:93], off offset:256 nt
	v_lshl_add_u64 v[2:3], v[2:3], 0, s[4:5]
	s_waitcnt vmcnt(15)
	v_lshlrev_b32_e32 v180, 16, v208
	v_and_b32_e32 v181, 0xffff0000, v208
	v_pk_fma_f32 v[82:83], v[82:83], v[148:149], v[180:181]
	v_lshlrev_b32_e32 v208, 16, v209
	v_and_b32_e32 v209, 0xffff0000, v209
	v_pk_fma_f32 v[84:85], v[84:85], v[146:147], v[208:209]
	v_lshlrev_b32_e32 v180, 16, v210
	v_and_b32_e32 v181, 0xffff0000, v210
	v_pk_fma_f32 v[78:79], v[78:79], v[144:145], v[180:181]
	v_lshlrev_b32_e32 v210, 16, v211
	v_and_b32_e32 v211, 0xffff0000, v211
	v_pk_fma_f32 v[80:81], v[80:81], v[142:143], v[210:211]
	v_cvt_pk_bf16_f32 v82, v82, v83
	v_cvt_pk_bf16_f32 v83, v84, v85
	v_cvt_pk_bf16_f32 v84, v78, v79
	v_cvt_pk_bf16_f32 v85, v80, v81
	global_store_dwordx4 v[2:3], v[82:85], off nt
	s_waitcnt vmcnt(15)
	v_lshlrev_b32_e32 v180, 16, v226
	v_and_b32_e32 v181, 0xffff0000, v226
	v_pk_fma_f32 v[74:75], v[74:75], v[140:141], v[180:181]
	v_lshlrev_b32_e32 v226, 16, v227
	v_and_b32_e32 v227, 0xffff0000, v227
	v_pk_fma_f32 v[76:77], v[76:77], v[138:139], v[226:227]
	v_lshlrev_b32_e32 v180, 16, v228
	v_and_b32_e32 v181, 0xffff0000, v228
	v_pk_fma_f32 v[70:71], v[70:71], v[136:137], v[180:181]
	v_lshlrev_b32_e32 v228, 16, v229
	v_and_b32_e32 v229, 0xffff0000, v229
	v_pk_fma_f32 v[72:73], v[72:73], v[134:135], v[228:229]
	v_cvt_pk_bf16_f32 v74, v74, v75
	v_cvt_pk_bf16_f32 v75, v76, v77
	v_cvt_pk_bf16_f32 v76, v70, v71
	v_cvt_pk_bf16_f32 v77, v72, v73
	global_store_dwordx4 v[2:3], v[74:77], off offset:256 nt
	v_lshl_add_u64 v[2:3], v[2:3], 0, vcc
	s_waitcnt vmcnt(15)
	v_lshlrev_b32_e32 v180, 16, v230
	v_and_b32_e32 v181, 0xffff0000, v230
	v_pk_fma_f32 v[66:67], v[66:67], v[148:149], v[180:181]
	v_lshlrev_b32_e32 v230, 16, v231
	v_and_b32_e32 v231, 0xffff0000, v231
	v_pk_fma_f32 v[68:69], v[68:69], v[146:147], v[230:231]
	v_lshlrev_b32_e32 v180, 16, v232
	v_and_b32_e32 v181, 0xffff0000, v232
	v_pk_fma_f32 v[62:63], v[62:63], v[144:145], v[180:181]
	v_lshlrev_b32_e32 v232, 16, v233
	v_and_b32_e32 v233, 0xffff0000, v233
	v_pk_fma_f32 v[64:65], v[64:65], v[142:143], v[232:233]
	v_cvt_pk_bf16_f32 v66, v66, v67
	v_cvt_pk_bf16_f32 v67, v68, v69
	v_cvt_pk_bf16_f32 v68, v62, v63
	v_cvt_pk_bf16_f32 v69, v64, v65
	global_store_dwordx4 v[2:3], v[66:69], off nt
	s_waitcnt vmcnt(15)
	v_lshlrev_b32_e32 v180, 16, v234
	v_and_b32_e32 v181, 0xffff0000, v234
	v_pk_fma_f32 v[58:59], v[58:59], v[140:141], v[180:181]
	v_lshlrev_b32_e32 v234, 16, v235
	v_and_b32_e32 v235, 0xffff0000, v235
	v_pk_fma_f32 v[60:61], v[60:61], v[138:139], v[234:235]
	v_lshlrev_b32_e32 v180, 16, v236
	v_and_b32_e32 v181, 0xffff0000, v236
	v_pk_fma_f32 v[54:55], v[54:55], v[136:137], v[180:181]
	v_lshlrev_b32_e32 v236, 16, v237
	v_and_b32_e32 v237, 0xffff0000, v237
	v_pk_fma_f32 v[56:57], v[56:57], v[134:135], v[236:237]
	v_cvt_pk_bf16_f32 v58, v58, v59
	v_cvt_pk_bf16_f32 v59, v60, v61
	v_cvt_pk_bf16_f32 v60, v54, v55
	v_cvt_pk_bf16_f32 v61, v56, v57
	global_store_dwordx4 v[2:3], v[58:61], off offset:256 nt
	v_lshl_add_u64 v[2:3], v[2:3], 0, s[4:5]
	s_waitcnt vmcnt(15)
; #define PG8_GAS __attribute__((address_space(1)))
; __device__ __forceinline__ unsigned cvtpk(float lo, float hi) { f32x2 v = {lo, hi}; bf16x2_t b = __builtin_convertvector(v, bf16x2_t); return __builtin_bit_cast(unsigned, b); }
; #define PG8_BAR __builtin_amdgcn_s_barrier()
;     __device__ __forceinline__ void operator()(const f32x4 (&acc)[2][2][4][2], const Unit& u, int wr, int wc, int fr, int fq) const {
;     ...
;                 for (int bj = 0; bj < 2; ++bj) {
;                     f32x4 b0, b1;
;                     if (basef) { b0 = __builtin_nontemporal_load((const PG8_GAS f32x4*)(basef + off + bj * HALF)); b1 = __builtin_nontemporal_load((const PG8_GAS f32x4*)(basef + off + bj * HALF + 4)); }
;                     else { const u32x4 w = __builtin_nontemporal_load((const PG8_GAS u32x4*)(baseb + off + bj * HALF));
;                         b0 = (f32x4){__uint_as_float(w.x << 16), __uint_as_float(w.x & 0xffff0000u), __uint_as_float(w.y << 16), __uint_as_float(w.y & 0xffff0000u)};
;                         b1 = (f32x4){__uint_as_float(w.z << 16), __uint_as_float(w.z & 0xffff0000u), __uint_as_float(w.w << 16), __uint_as_float(w.w & 0xffff0000u)}; }
;                     const f32x4 o0 = b0 + gv[bj][0] * acc[ai][bj][m][0], o1 = b1 + gv[bj][1] * acc[ai][bj][m][1];
;                     u32x4 w; w.x = cvtpk(o0[0], o0[1]); w.y = cvtpk(o0[2], o0[3]); w.z = cvtpk(o1[0], o1[1]); w.w = cvtpk(o1[2], o1[3]);
;                     __builtin_nontemporal_store(w, (PG8_GAS u32x4*)(out + off + bj * HALF));
; template <class Epi, class Sched, bool ALIGN_EPI = false, bool SP2 = false>
; __device__ __forceinline__ void gemm_phase(PG8_LAS unsigned char* lds, const Gemm g, const Sched& S, const Epi& E, const int tid) {
;     ...
;         if constexpr (ALIGN_EPI) { if (wr == 0) PG8_BAR; }
;         if constexpr (!Epi::AFTER_DRAIN) { E(acc, cur, wr, wc, fr, fq); S.done(cur); }
;         if (!has_next) break;
; #pragma unroll
;         for (int a = 0; a < 2; ++a)
; #pragma unroll
;             for (int b = 0; b < 2; ++b)
; #pragma unroll
;                 for (int m = 0; m < 4; ++m)
; #pragma unroll
;                     for (int n = 0; n < 2; ++n) acc[a][b][m][n] = (f32x4){0.f, 0.f, 0.f, 0.f};
;         cur = nxt; cA = nA; cB = nB; ++ui;
;         if constexpr (ALIGN_EPI) { if (wr == 1) PG8_BAR; }
;     }
	v_lshlrev_b32_e32 v180, 16, v238
	v_and_b32_e32 v181, 0xffff0000, v238
	v_pk_fma_f32 v[50:51], v[50:51], v[148:149], v[180:181]
	v_lshlrev_b32_e32 v238, 16, v239
	v_and_b32_e32 v239, 0xffff0000, v239
	v_pk_fma_f32 v[52:53], v[52:53], v[146:147], v[238:239]
	v_lshlrev_b32_e32 v180, 16, v240
	v_and_b32_e32 v181, 0xffff0000, v240
	v_pk_fma_f32 v[46:47], v[46:47], v[144:145], v[180:181]
	v_lshlrev_b32_e32 v240, 16, v241
	v_and_b32_e32 v241, 0xffff0000, v241
	v_pk_fma_f32 v[48:49], v[48:49], v[142:143], v[240:241]
	v_cvt_pk_bf16_f32 v50, v50, v51
	v_cvt_pk_bf16_f32 v51, v52, v53
	v_cvt_pk_bf16_f32 v52, v46, v47
	v_cvt_pk_bf16_f32 v53, v48, v49
	global_store_dwordx4 v[2:3], v[50:53], off nt
	s_waitcnt vmcnt(15)
	v_lshlrev_b32_e32 v180, 16, v242
	v_and_b32_e32 v181, 0xffff0000, v242
	v_pk_fma_f32 v[42:43], v[42:43], v[140:141], v[180:181]
	v_lshlrev_b32_e32 v242, 16, v243
	v_and_b32_e32 v243, 0xffff0000, v243
	v_pk_fma_f32 v[44:45], v[44:45], v[138:139], v[242:243]
	v_lshlrev_b32_e32 v180, 16, v244
	v_and_b32_e32 v181, 0xffff0000, v244
	v_pk_fma_f32 v[38:39], v[38:39], v[136:137], v[180:181]
	v_lshlrev_b32_e32 v244, 16, v245
	v_and_b32_e32 v245, 0xffff0000, v245
	v_pk_fma_f32 v[40:41], v[40:41], v[134:135], v[244:245]
	v_cvt_pk_bf16_f32 v42, v42, v43
	v_cvt_pk_bf16_f32 v43, v44, v45
	v_cvt_pk_bf16_f32 v44, v38, v39
	v_cvt_pk_bf16_f32 v45, v40, v41
	global_store_dwordx4 v[2:3], v[42:45], off offset:256 nt
	v_lshl_add_u64 v[2:3], v[2:3], 0, s[4:5]
	s_waitcnt vmcnt(15)
	v_lshlrev_b32_e32 v180, 16, v246
	v_and_b32_e32 v181, 0xffff0000, v246
	v_pk_fma_f32 v[34:35], v[34:35], v[148:149], v[180:181]
	v_lshlrev_b32_e32 v246, 16, v247
	v_and_b32_e32 v247, 0xffff0000, v247
	v_pk_fma_f32 v[36:37], v[36:37], v[146:147], v[246:247]
	v_lshlrev_b32_e32 v180, 16, v248
	v_and_b32_e32 v181, 0xffff0000, v248
	v_pk_fma_f32 v[30:31], v[30:31], v[144:145], v[180:181]
	v_lshlrev_b32_e32 v248, 16, v249
	v_and_b32_e32 v249, 0xffff0000, v249
	v_pk_fma_f32 v[32:33], v[32:33], v[142:143], v[248:249]
	v_cvt_pk_bf16_f32 v34, v34, v35
	v_cvt_pk_bf16_f32 v35, v36, v37
	v_cvt_pk_bf16_f32 v36, v30, v31
	v_cvt_pk_bf16_f32 v37, v32, v33
	global_store_dwordx4 v[2:3], v[34:37], off nt
	s_waitcnt vmcnt(15)
	v_lshlrev_b32_e32 v180, 16, v250
	v_and_b32_e32 v181, 0xffff0000, v250
	v_pk_fma_f32 v[26:27], v[26:27], v[140:141], v[180:181]
	v_lshlrev_b32_e32 v250, 16, v251
	v_and_b32_e32 v251, 0xffff0000, v251
	v_pk_fma_f32 v[28:29], v[28:29], v[138:139], v[250:251]
	v_lshlrev_b32_e32 v180, 16, v252
	v_and_b32_e32 v181, 0xffff0000, v252
	v_pk_fma_f32 v[22:23], v[22:23], v[136:137], v[180:181]
	v_lshlrev_b32_e32 v252, 16, v253
	v_and_b32_e32 v253, 0xffff0000, v253
	v_pk_fma_f32 v[24:25], v[24:25], v[134:135], v[252:253]
	v_cvt_pk_bf16_f32 v26, v26, v27
	v_cvt_pk_bf16_f32 v27, v28, v29
	v_cvt_pk_bf16_f32 v28, v22, v23
	v_cvt_pk_bf16_f32 v29, v24, v25
	global_store_dwordx4 v[2:3], v[26:29], off offset:256 nt
	v_lshl_add_u64 v[2:3], v[2:3], 0, s[4:5]
	s_waitcnt vmcnt(15)
	v_lshlrev_b32_e32 v180, 16, v150
	v_and_b32_e32 v181, 0xffff0000, v150
	v_pk_fma_f32 v[18:19], v[18:19], v[148:149], v[180:181]
	v_lshlrev_b32_e32 v150, 16, v151
	v_and_b32_e32 v151, 0xffff0000, v151
	v_pk_fma_f32 v[20:21], v[20:21], v[146:147], v[150:151]
	v_lshlrev_b32_e32 v180, 16, v152
	v_and_b32_e32 v181, 0xffff0000, v152
	v_pk_fma_f32 v[14:15], v[14:15], v[144:145], v[180:181]
	v_lshlrev_b32_e32 v152, 16, v153
	v_and_b32_e32 v153, 0xffff0000, v153
	v_pk_fma_f32 v[16:17], v[16:17], v[142:143], v[152:153]
	v_cvt_pk_bf16_f32 v18, v18, v19
	v_cvt_pk_bf16_f32 v19, v20, v21
	v_cvt_pk_bf16_f32 v20, v14, v15
	v_cvt_pk_bf16_f32 v21, v16, v17
	global_store_dwordx4 v[2:3], v[18:21], off nt
	s_waitcnt vmcnt(15)
	v_lshlrev_b32_e32 v180, 16, v126
	v_and_b32_e32 v181, 0xffff0000, v126
	v_pk_fma_f32 v[10:11], v[10:11], v[140:141], v[180:181]
	v_lshlrev_b32_e32 v126, 16, v127
	v_and_b32_e32 v127, 0xffff0000, v127
	v_pk_fma_f32 v[12:13], v[12:13], v[138:139], v[126:127]
	v_lshlrev_b32_e32 v180, 16, v128
	v_and_b32_e32 v181, 0xffff0000, v128
	v_pk_fma_f32 v[6:7], v[6:7], v[136:137], v[180:181]
	v_lshlrev_b32_e32 v128, 16, v129
	v_and_b32_e32 v129, 0xffff0000, v129
	v_pk_fma_f32 v[8:9], v[8:9], v[134:135], v[128:129]
	v_cvt_pk_bf16_f32 v10, v10, v11
	v_cvt_pk_bf16_f32 v11, v12, v13
	v_cvt_pk_bf16_f32 v12, v6, v7
	v_cvt_pk_bf16_f32 v13, v8, v9
	s_and_b64 vcc, exec, s[6:7]
	s_mov_b64 s[4:5], -1
	global_store_dwordx4 v[2:3], v[10:13], off offset:256 nt
.Lres_epi_tail:
	s_cbranch_vccnz .LBB0_611
	s_andn2_b64 vcc, exec, s[76:77]
	s_cbranch_vccnz .LBB0_610
	s_barrier
	s_branch .LBB0_610
